# one static s_setprio 1 for waves 4-7 before the P5 and P6' K-loops, per-segment flips in those loops deleted, priority 0 restored at loop exit; rest as v058
# speedup vs baseline: 1.0039x; 1.0017x over previous
.LBB0_506:
	s_add_u32 s42, s42, 0x80080
	s_addc_u32 s43, s43, 0
	s_add_u32 s17, s44, 0x100
	v_mov_b32_e32 v0, 0
	s_addc_u32 s21, s45, 0
	s_mov_b32 s52, -2
	v_mov_b32_e32 v1, v0
	v_mov_b32_e32 v2, v0
	v_mov_b32_e32 v3, v0
	v_mov_b32_e32 v4, v0
	v_mov_b32_e32 v5, v0
	v_mov_b32_e32 v6, v0
	v_mov_b32_e32 v7, v0
	v_mov_b32_e32 v16, v0
	v_mov_b32_e32 v17, v0
	v_mov_b32_e32 v18, v0
	v_mov_b32_e32 v19, v0
	v_mov_b32_e32 v20, v0
	v_mov_b32_e32 v21, v0
	v_mov_b32_e32 v22, v0
	v_mov_b32_e32 v23, v0
	v_mov_b32_e32 v32, v0
	v_mov_b32_e32 v33, v0
	v_mov_b32_e32 v34, v0
	v_mov_b32_e32 v35, v0
	v_mov_b32_e32 v36, v0
	v_mov_b32_e32 v37, v0
	v_mov_b32_e32 v38, v0
	v_mov_b32_e32 v39, v0
	v_mov_b32_e32 v48, v0
	v_mov_b32_e32 v49, v0
	v_mov_b32_e32 v50, v0
	v_mov_b32_e32 v51, v0
	v_mov_b32_e32 v52, v0
	v_mov_b32_e32 v53, v0
	v_mov_b32_e32 v54, v0
	v_mov_b32_e32 v55, v0
	v_mov_b32_e32 v8, v0
	v_mov_b32_e32 v9, v0
	v_mov_b32_e32 v10, v0
	v_mov_b32_e32 v11, v0
	v_mov_b32_e32 v12, v0
	v_mov_b32_e32 v13, v0
	v_mov_b32_e32 v14, v0
	v_mov_b32_e32 v15, v0
	v_mov_b32_e32 v24, v0
	v_mov_b32_e32 v25, v0
	v_mov_b32_e32 v26, v0
	v_mov_b32_e32 v27, v0
	v_mov_b32_e32 v28, v0
	v_mov_b32_e32 v29, v0
	v_mov_b32_e32 v30, v0
	v_mov_b32_e32 v31, v0
	v_mov_b32_e32 v40, v0
	v_mov_b32_e32 v41, v0
	v_mov_b32_e32 v42, v0
	v_mov_b32_e32 v43, v0
	v_mov_b32_e32 v44, v0
	v_mov_b32_e32 v45, v0
	v_mov_b32_e32 v46, v0
	v_mov_b32_e32 v47, v0
	v_mov_b32_e32 v56, v0
	v_mov_b32_e32 v57, v0
	v_mov_b32_e32 v58, v0
	v_mov_b32_e32 v59, v0
	v_mov_b32_e32 v60, v0
	v_mov_b32_e32 v61, v0
	v_mov_b32_e32 v62, v0
	v_mov_b32_e32 v63, v0
	v_mov_b32_e32 v64, v0
	v_mov_b32_e32 v65, v0
	v_mov_b32_e32 v66, v0
	v_mov_b32_e32 v67, v0
	v_mov_b32_e32 v68, v0
	v_mov_b32_e32 v69, v0
	v_mov_b32_e32 v70, v0
	v_mov_b32_e32 v71, v0
	v_mov_b32_e32 v80, v0
	v_mov_b32_e32 v81, v0
	v_mov_b32_e32 v82, v0
	v_mov_b32_e32 v83, v0
	v_mov_b32_e32 v84, v0
	v_mov_b32_e32 v85, v0
	v_mov_b32_e32 v86, v0
	v_mov_b32_e32 v87, v0
	v_mov_b32_e32 v96, v0
	v_mov_b32_e32 v97, v0
	v_mov_b32_e32 v98, v0
	v_mov_b32_e32 v99, v0
	v_mov_b32_e32 v100, v0
	v_mov_b32_e32 v101, v0
	v_mov_b32_e32 v102, v0
	v_mov_b32_e32 v103, v0
	v_mov_b32_e32 v112, v0
	v_mov_b32_e32 v113, v0
	v_mov_b32_e32 v114, v0
	v_mov_b32_e32 v115, v0
	v_mov_b32_e32 v116, v0
	v_mov_b32_e32 v117, v0
	v_mov_b32_e32 v118, v0
	v_mov_b32_e32 v119, v0
	v_mov_b32_e32 v72, v0
	v_mov_b32_e32 v73, v0
	v_mov_b32_e32 v74, v0
	v_mov_b32_e32 v75, v0
	v_mov_b32_e32 v76, v0
	v_mov_b32_e32 v77, v0
	v_mov_b32_e32 v78, v0
	v_mov_b32_e32 v79, v0
	v_mov_b32_e32 v88, v0
	v_mov_b32_e32 v89, v0
	v_mov_b32_e32 v90, v0
	v_mov_b32_e32 v91, v0
	v_mov_b32_e32 v92, v0
	v_mov_b32_e32 v93, v0
	v_mov_b32_e32 v94, v0
	v_mov_b32_e32 v95, v0
	v_mov_b32_e32 v104, v0
	v_mov_b32_e32 v105, v0
	v_mov_b32_e32 v106, v0
	v_mov_b32_e32 v107, v0
	v_mov_b32_e32 v108, v0
	v_mov_b32_e32 v109, v0
	v_mov_b32_e32 v110, v0
	v_mov_b32_e32 v111, v0
	v_mov_b32_e32 v120, v0
	v_mov_b32_e32 v121, v0
	v_mov_b32_e32 v122, v0
	v_mov_b32_e32 v123, v0
	v_mov_b32_e32 v124, v0
	v_mov_b32_e32 v125, v0
	v_mov_b32_e32 v126, v0
	v_mov_b32_e32 v127, v0
	v_readlane_b32 s54, v254, 6
	s_nop 3
	s_cmp_ge_u32 s54, 0x100
	s_cbranch_scc0 .Lsprio_p5
	s_setprio 1
.Lsprio_p5:
.LBB0_507:
	ds_read_b128 v[166:169], v163
	ds_read_b128 v[170:173], v163 offset:1024
	ds_read_b128 v[174:177], v163 offset:2048
	ds_read_b128 v[178:181], v163 offset:3072
	ds_read_b128 v[182:185], v164
	ds_read_b128 v[188:191], v164 offset:1024
	ds_read_b128 v[192:195], v164 offset:2048
	ds_read_b128 v[196:199], v164 offset:3072
	s_add_u32 s44, s42, 0xfff80080
	s_addc_u32 s45, s43, -1
	s_cmp_eq_u32 s52, 28
	s_cselect_b32 s47, s7, s45
	s_cselect_b32 s46, s6, s44
	s_cselect_b32 s45, s23, s21
	s_cselect_b32 s44, s22, s17
	s_add_u32 s54, s44, 0x80000
	s_addc_u32 s55, s45, 0
	s_mov_b32 m0, s94
	ds_read_b128 v[200:203], v165
	ds_read_b128 v[204:207], v165 offset:1024
	ds_read_b128 v[208:211], v165 offset:2048
	ds_read_b128 v[212:215], v165 offset:3072
	ds_read_b128 v[216:219], v165 offset:4096
	ds_read_b128 v[220:223], v165 offset:5120
	ds_read_b128 v[224:227], v165 offset:6144
	ds_read_b128 v[228:231], v165 offset:7168
	global_load_lds_dwordx4 v152, s[42:43]
	s_mov_b32 m0, s95
	s_nop 0
	global_load_lds_dwordx4 v154, s[42:43]
	s_waitcnt vmcnt(8)
	s_waitcnt lgkmcnt(0)
	s_barrier
	s_waitcnt lgkmcnt(0)
	v_mfma_f32_16x16x32_bf16 v[124:127], v[166:169], v[200:203], v[124:127]
	v_mfma_f32_16x16x32_bf16 v[120:123], v[174:177], v[200:203], v[120:123]
	v_mfma_f32_16x16x32_bf16 v[108:111], v[166:169], v[208:211], v[108:111]
	v_mfma_f32_16x16x32_bf16 v[104:107], v[174:177], v[208:211], v[104:107]
	v_mfma_f32_16x16x32_bf16 v[92:95], v[166:169], v[216:219], v[92:95]
	v_mfma_f32_16x16x32_bf16 v[88:91], v[174:177], v[216:219], v[88:91]
	v_mfma_f32_16x16x32_bf16 v[76:79], v[166:169], v[224:227], v[76:79]
	v_mfma_f32_16x16x32_bf16 v[72:75], v[174:177], v[224:227], v[72:75]
	v_mfma_f32_16x16x32_bf16 v[124:127], v[170:173], v[204:207], v[124:127]
	v_mfma_f32_16x16x32_bf16 v[120:123], v[178:181], v[204:207], v[120:123]
	v_mfma_f32_16x16x32_bf16 v[108:111], v[170:173], v[212:215], v[108:111]
	v_mfma_f32_16x16x32_bf16 v[104:107], v[178:181], v[212:215], v[104:107]
	v_mfma_f32_16x16x32_bf16 v[92:95], v[170:173], v[220:223], v[92:95]
	v_mfma_f32_16x16x32_bf16 v[88:91], v[178:181], v[220:223], v[88:91]
	v_mfma_f32_16x16x32_bf16 v[76:79], v[170:173], v[228:231], v[76:79]
	v_mfma_f32_16x16x32_bf16 v[72:75], v[178:181], v[228:231], v[72:75]
	v_mfma_f32_16x16x32_bf16 v[116:119], v[182:185], v[200:203], v[116:119]
	v_mfma_f32_16x16x32_bf16 v[112:115], v[192:195], v[200:203], v[112:115]
	v_mfma_f32_16x16x32_bf16 v[100:103], v[182:185], v[208:211], v[100:103]
	v_mfma_f32_16x16x32_bf16 v[96:99], v[192:195], v[208:211], v[96:99]
	v_mfma_f32_16x16x32_bf16 v[84:87], v[182:185], v[216:219], v[84:87]
	v_mfma_f32_16x16x32_bf16 v[80:83], v[192:195], v[216:219], v[80:83]
	v_mfma_f32_16x16x32_bf16 v[68:71], v[182:185], v[224:227], v[68:71]
	v_mfma_f32_16x16x32_bf16 v[64:67], v[192:195], v[224:227], v[64:67]
	v_mfma_f32_16x16x32_bf16 v[116:119], v[188:191], v[204:207], v[116:119]
	v_mfma_f32_16x16x32_bf16 v[112:115], v[196:199], v[204:207], v[112:115]
	v_mfma_f32_16x16x32_bf16 v[100:103], v[188:191], v[212:215], v[100:103]
	v_mfma_f32_16x16x32_bf16 v[96:99], v[196:199], v[212:215], v[96:99]
	v_mfma_f32_16x16x32_bf16 v[84:87], v[188:191], v[220:223], v[84:87]
	v_mfma_f32_16x16x32_bf16 v[80:83], v[196:199], v[220:223], v[80:83]
	v_mfma_f32_16x16x32_bf16 v[68:71], v[188:191], v[228:231], v[68:71]
	v_mfma_f32_16x16x32_bf16 v[64:67], v[196:199], v[228:231], v[64:67]
	s_barrier
	s_mov_b32 m0, s96
	s_add_u32 s98, s46, 0x80000
	s_addc_u32 s99, s47, 0
	ds_read_b128 v[200:203], v165 offset:16384
	ds_read_b128 v[204:207], v165 offset:17408
	ds_read_b128 v[208:211], v165 offset:18432
	ds_read_b128 v[212:215], v165 offset:19456
	ds_read_b128 v[216:219], v165 offset:20480
	ds_read_b128 v[220:223], v165 offset:21504
	ds_read_b128 v[224:227], v165 offset:22528
	ds_read_b128 v[228:231], v165 offset:23552
	global_load_lds_dwordx4 v130, s[44:45]
	s_mov_b32 m0, s97
	s_nop 0
	global_load_lds_dwordx4 v134, s[44:45]
	s_mov_b32 m0, s91
	s_nop 0
	global_load_lds_dwordx4 v130, s[54:55]
	s_mov_b32 m0, s26
	s_nop 0
	global_load_lds_dwordx4 v134, s[54:55]
	s_mov_b32 m0, s33
	s_nop 0
	global_load_lds_dwordx4 v128, s[46:47]
	s_mov_b32 m0, s88
	s_nop 0
	global_load_lds_dwordx4 v132, s[46:47]
	s_waitcnt vmcnt(8)
	s_waitcnt lgkmcnt(0)
	s_barrier
	s_waitcnt lgkmcnt(0)
	v_mfma_f32_16x16x32_bf16 v[60:63], v[166:169], v[200:203], v[60:63]
	v_mfma_f32_16x16x32_bf16 v[56:59], v[174:177], v[200:203], v[56:59]
	v_mfma_f32_16x16x32_bf16 v[44:47], v[166:169], v[208:211], v[44:47]
	v_mfma_f32_16x16x32_bf16 v[40:43], v[174:177], v[208:211], v[40:43]
	v_mfma_f32_16x16x32_bf16 v[28:31], v[166:169], v[216:219], v[28:31]
	v_mfma_f32_16x16x32_bf16 v[24:27], v[174:177], v[216:219], v[24:27]
	v_mfma_f32_16x16x32_bf16 v[12:15], v[166:169], v[224:227], v[12:15]
	v_mfma_f32_16x16x32_bf16 v[8:11], v[174:177], v[224:227], v[8:11]
	v_mfma_f32_16x16x32_bf16 v[60:63], v[170:173], v[204:207], v[60:63]
	v_mfma_f32_16x16x32_bf16 v[56:59], v[178:181], v[204:207], v[56:59]
	v_mfma_f32_16x16x32_bf16 v[44:47], v[170:173], v[212:215], v[44:47]
	v_mfma_f32_16x16x32_bf16 v[40:43], v[178:181], v[212:215], v[40:43]
	v_mfma_f32_16x16x32_bf16 v[28:31], v[170:173], v[220:223], v[28:31]
	v_mfma_f32_16x16x32_bf16 v[24:27], v[178:181], v[220:223], v[24:27]
	v_mfma_f32_16x16x32_bf16 v[12:15], v[170:173], v[228:231], v[12:15]
	v_mfma_f32_16x16x32_bf16 v[8:11], v[178:181], v[228:231], v[8:11]
	v_mfma_f32_16x16x32_bf16 v[52:55], v[182:185], v[200:203], v[52:55]
	v_mfma_f32_16x16x32_bf16 v[48:51], v[192:195], v[200:203], v[48:51]
	v_mfma_f32_16x16x32_bf16 v[36:39], v[182:185], v[208:211], v[36:39]
	v_mfma_f32_16x16x32_bf16 v[32:35], v[192:195], v[208:211], v[32:35]
	v_mfma_f32_16x16x32_bf16 v[20:23], v[182:185], v[216:219], v[20:23]
	v_mfma_f32_16x16x32_bf16 v[16:19], v[192:195], v[216:219], v[16:19]
	v_mfma_f32_16x16x32_bf16 v[4:7], v[182:185], v[224:227], v[4:7]
	v_mfma_f32_16x16x32_bf16 v[0:3], v[192:195], v[224:227], v[0:3]
	v_mfma_f32_16x16x32_bf16 v[52:55], v[188:191], v[204:207], v[52:55]
	v_mfma_f32_16x16x32_bf16 v[48:51], v[196:199], v[204:207], v[48:51]
	v_mfma_f32_16x16x32_bf16 v[36:39], v[188:191], v[212:215], v[36:39]
	v_mfma_f32_16x16x32_bf16 v[32:35], v[196:199], v[212:215], v[32:35]
	v_mfma_f32_16x16x32_bf16 v[20:23], v[188:191], v[220:223], v[20:23]
	v_mfma_f32_16x16x32_bf16 v[16:19], v[196:199], v[220:223], v[16:19]
	v_mfma_f32_16x16x32_bf16 v[4:7], v[188:191], v[228:231], v[4:7]
	v_mfma_f32_16x16x32_bf16 v[0:3], v[196:199], v[228:231], v[0:3]
	s_barrier
	v_add_u32_e32 v178, s29, v162
	v_add_u32_e32 v187, s41, v162
	ds_read_b128 v[166:169], v178
	ds_read_b128 v[170:173], v178 offset:1024
	ds_read_b128 v[174:177], v178 offset:2048
	ds_read_b128 v[178:181], v178 offset:3072
	ds_read_b128 v[182:185], v187
	ds_read_b128 v[188:191], v187 offset:1024
	ds_read_b128 v[192:195], v187 offset:2048
	ds_read_b128 v[196:199], v187 offset:3072
	s_mov_b32 m0, s89
	s_add_u32 s100, s44, 0x80
	s_addc_u32 s101, s45, 0
	ds_read_b128 v[200:203], v165 offset:32768
	ds_read_b128 v[204:207], v165 offset:33792
	ds_read_b128 v[208:211], v165 offset:34816
	ds_read_b128 v[212:215], v165 offset:35840
	ds_read_b128 v[216:219], v165 offset:36864
	ds_read_b128 v[220:223], v165 offset:37888
	ds_read_b128 v[224:227], v165 offset:38912
	ds_read_b128 v[228:231], v165 offset:39936
	global_load_lds_dwordx4 v128, s[98:99]
	s_mov_b32 m0, s90
	s_add_u32 s54, s44, 0x80080
	s_addc_u32 s55, s45, 0
	global_load_lds_dwordx4 v132, s[98:99]
	s_add_u32 s98, s46, 0x80
	s_addc_u32 s99, s47, 0
	s_waitcnt vmcnt(8)
	s_waitcnt lgkmcnt(0)
	s_barrier
	s_waitcnt lgkmcnt(0)
	v_mfma_f32_16x16x32_bf16 v[124:127], v[166:169], v[200:203], v[124:127]
	v_mfma_f32_16x16x32_bf16 v[120:123], v[174:177], v[200:203], v[120:123]
	v_mfma_f32_16x16x32_bf16 v[108:111], v[166:169], v[208:211], v[108:111]
	v_mfma_f32_16x16x32_bf16 v[104:107], v[174:177], v[208:211], v[104:107]
	v_mfma_f32_16x16x32_bf16 v[92:95], v[166:169], v[216:219], v[92:95]
	v_mfma_f32_16x16x32_bf16 v[88:91], v[174:177], v[216:219], v[88:91]
	v_mfma_f32_16x16x32_bf16 v[76:79], v[166:169], v[224:227], v[76:79]
	v_mfma_f32_16x16x32_bf16 v[72:75], v[174:177], v[224:227], v[72:75]
	v_mfma_f32_16x16x32_bf16 v[124:127], v[170:173], v[204:207], v[124:127]
	v_mfma_f32_16x16x32_bf16 v[120:123], v[178:181], v[204:207], v[120:123]
	v_mfma_f32_16x16x32_bf16 v[108:111], v[170:173], v[212:215], v[108:111]
	v_mfma_f32_16x16x32_bf16 v[104:107], v[178:181], v[212:215], v[104:107]
	v_mfma_f32_16x16x32_bf16 v[92:95], v[170:173], v[220:223], v[92:95]
	v_mfma_f32_16x16x32_bf16 v[88:91], v[178:181], v[220:223], v[88:91]
	v_mfma_f32_16x16x32_bf16 v[76:79], v[170:173], v[228:231], v[76:79]
	v_mfma_f32_16x16x32_bf16 v[72:75], v[178:181], v[228:231], v[72:75]
	v_mfma_f32_16x16x32_bf16 v[116:119], v[182:185], v[200:203], v[116:119]
	v_mfma_f32_16x16x32_bf16 v[112:115], v[192:195], v[200:203], v[112:115]
	v_mfma_f32_16x16x32_bf16 v[100:103], v[182:185], v[208:211], v[100:103]
	v_mfma_f32_16x16x32_bf16 v[96:99], v[192:195], v[208:211], v[96:99]
	v_mfma_f32_16x16x32_bf16 v[84:87], v[182:185], v[216:219], v[84:87]
	v_mfma_f32_16x16x32_bf16 v[80:83], v[192:195], v[216:219], v[80:83]
	v_mfma_f32_16x16x32_bf16 v[68:71], v[182:185], v[224:227], v[68:71]
	v_mfma_f32_16x16x32_bf16 v[64:67], v[192:195], v[224:227], v[64:67]
	v_mfma_f32_16x16x32_bf16 v[116:119], v[188:191], v[204:207], v[116:119]
	v_mfma_f32_16x16x32_bf16 v[112:115], v[196:199], v[204:207], v[112:115]
	v_mfma_f32_16x16x32_bf16 v[100:103], v[188:191], v[212:215], v[100:103]
	v_mfma_f32_16x16x32_bf16 v[96:99], v[196:199], v[212:215], v[96:99]
	v_mfma_f32_16x16x32_bf16 v[84:87], v[188:191], v[220:223], v[84:87]
	v_mfma_f32_16x16x32_bf16 v[80:83], v[196:199], v[220:223], v[80:83]
	v_mfma_f32_16x16x32_bf16 v[68:71], v[188:191], v[228:231], v[68:71]
	v_mfma_f32_16x16x32_bf16 v[64:67], v[196:199], v[228:231], v[64:67]
	s_barrier
	s_mov_b32 m0, s27
	s_nop 0
	ds_read_b128 v[200:203], v165 offset:49152
	ds_read_b128 v[204:207], v165 offset:50176
	ds_read_b128 v[208:211], v165 offset:51200
	ds_read_b128 v[212:215], v165 offset:52224
	ds_read_b128 v[216:219], v165 offset:53248
	ds_read_b128 v[220:223], v165 offset:54272
	ds_read_b128 v[224:227], v165 offset:55296
	ds_read_b128 v[228:231], v165 offset:56320
	global_load_lds_dwordx4 v130, s[100:101]
	s_mov_b32 m0, s34
	s_nop 0
	global_load_lds_dwordx4 v134, s[100:101]
	s_mov_b32 m0, s35
	s_nop 0
	global_load_lds_dwordx4 v130, s[54:55]
	s_mov_b32 m0, s28
	s_nop 0
	global_load_lds_dwordx4 v134, s[54:55]
	s_mov_b32 m0, s92
	s_nop 0
	global_load_lds_dwordx4 v128, s[98:99]
	s_mov_b32 m0, s93
	s_nop 0
	global_load_lds_dwordx4 v132, s[98:99]
	s_waitcnt vmcnt(8)
	s_waitcnt lgkmcnt(0)
	s_barrier
	s_waitcnt lgkmcnt(0)
	v_mfma_f32_16x16x32_bf16 v[60:63], v[166:169], v[200:203], v[60:63]
	v_mfma_f32_16x16x32_bf16 v[56:59], v[174:177], v[200:203], v[56:59]
	v_mfma_f32_16x16x32_bf16 v[44:47], v[166:169], v[208:211], v[44:47]
	v_mfma_f32_16x16x32_bf16 v[40:43], v[174:177], v[208:211], v[40:43]
	v_mfma_f32_16x16x32_bf16 v[28:31], v[166:169], v[216:219], v[28:31]
	v_mfma_f32_16x16x32_bf16 v[24:27], v[174:177], v[216:219], v[24:27]
	v_mfma_f32_16x16x32_bf16 v[12:15], v[166:169], v[224:227], v[12:15]
	v_mfma_f32_16x16x32_bf16 v[8:11], v[174:177], v[224:227], v[8:11]
	v_mfma_f32_16x16x32_bf16 v[60:63], v[170:173], v[204:207], v[60:63]
	v_mfma_f32_16x16x32_bf16 v[56:59], v[178:181], v[204:207], v[56:59]
	v_mfma_f32_16x16x32_bf16 v[44:47], v[170:173], v[212:215], v[44:47]
	v_mfma_f32_16x16x32_bf16 v[40:43], v[178:181], v[212:215], v[40:43]
	v_mfma_f32_16x16x32_bf16 v[28:31], v[170:173], v[220:223], v[28:31]
	v_mfma_f32_16x16x32_bf16 v[24:27], v[178:181], v[220:223], v[24:27]
	v_mfma_f32_16x16x32_bf16 v[12:15], v[170:173], v[228:231], v[12:15]
	v_mfma_f32_16x16x32_bf16 v[8:11], v[178:181], v[228:231], v[8:11]
	v_mfma_f32_16x16x32_bf16 v[52:55], v[182:185], v[200:203], v[52:55]
	v_mfma_f32_16x16x32_bf16 v[48:51], v[192:195], v[200:203], v[48:51]
	v_mfma_f32_16x16x32_bf16 v[36:39], v[182:185], v[208:211], v[36:39]
	v_mfma_f32_16x16x32_bf16 v[32:35], v[192:195], v[208:211], v[32:35]
	v_mfma_f32_16x16x32_bf16 v[20:23], v[182:185], v[216:219], v[20:23]
	v_mfma_f32_16x16x32_bf16 v[16:19], v[192:195], v[216:219], v[16:19]
	v_mfma_f32_16x16x32_bf16 v[4:7], v[182:185], v[224:227], v[4:7]
	v_mfma_f32_16x16x32_bf16 v[0:3], v[192:195], v[224:227], v[0:3]
	v_mfma_f32_16x16x32_bf16 v[52:55], v[188:191], v[204:207], v[52:55]
	v_mfma_f32_16x16x32_bf16 v[48:51], v[196:199], v[204:207], v[48:51]
	v_mfma_f32_16x16x32_bf16 v[36:39], v[188:191], v[212:215], v[36:39]
	v_mfma_f32_16x16x32_bf16 v[32:35], v[196:199], v[212:215], v[32:35]
	v_mfma_f32_16x16x32_bf16 v[20:23], v[188:191], v[220:223], v[20:23]
	v_mfma_f32_16x16x32_bf16 v[16:19], v[196:199], v[220:223], v[16:19]
	v_mfma_f32_16x16x32_bf16 v[4:7], v[188:191], v[228:231], v[4:7]
	v_mfma_f32_16x16x32_bf16 v[0:3], v[196:199], v[228:231], v[0:3]
	s_barrier
	s_add_i32 s52, s52, 2
	s_add_u32 s42, s42, 0x100
	s_addc_u32 s43, s43, 0
	s_add_u32 s17, s17, 0x100
	s_addc_u32 s21, s21, 0
	s_cmp_gt_u32 s52, 29
	s_cbranch_scc0 .LBB0_507
	s_setprio 0
	s_and_b64 vcc, exec, s[78:79]
	s_cbranch_vccz .LBB0_510
	s_barrier

.LBB0_673:
	s_and_b64 s[30:31], s[22:23], exec
	s_cselect_b32 s3, s11, s25
	s_cselect_b32 s29, s10, s24
	s_add_u32 s24, s24, 0xc000
	v_mov_b32_e32 v0, 0
	s_addc_u32 s25, s25, 0
	s_mov_b32 s45, -2
	s_mov_b64 s[30:31], s[20:21]
	v_mov_b32_e32 v1, v0
	v_mov_b32_e32 v2, v0
	v_mov_b32_e32 v3, v0
	v_mov_b32_e32 v4, v0
	v_mov_b32_e32 v5, v0
	v_mov_b32_e32 v6, v0
	v_mov_b32_e32 v7, v0
	v_mov_b32_e32 v16, v0
	v_mov_b32_e32 v17, v0
	v_mov_b32_e32 v18, v0
	v_mov_b32_e32 v19, v0
	v_mov_b32_e32 v20, v0
	v_mov_b32_e32 v21, v0
	v_mov_b32_e32 v22, v0
	v_mov_b32_e32 v23, v0
	v_mov_b32_e32 v32, v0
	v_mov_b32_e32 v33, v0
	v_mov_b32_e32 v34, v0
	v_mov_b32_e32 v35, v0
	v_mov_b32_e32 v36, v0
	v_mov_b32_e32 v37, v0
	v_mov_b32_e32 v38, v0
	v_mov_b32_e32 v39, v0
	v_mov_b32_e32 v48, v0
	v_mov_b32_e32 v49, v0
	v_mov_b32_e32 v50, v0
	v_mov_b32_e32 v51, v0
	v_mov_b32_e32 v52, v0
	v_mov_b32_e32 v53, v0
	v_mov_b32_e32 v54, v0
	v_mov_b32_e32 v55, v0
	v_mov_b32_e32 v8, v0
	v_mov_b32_e32 v9, v0
	v_mov_b32_e32 v10, v0
	v_mov_b32_e32 v11, v0
	v_mov_b32_e32 v12, v0
	v_mov_b32_e32 v13, v0
	v_mov_b32_e32 v14, v0
	v_mov_b32_e32 v15, v0
	v_mov_b32_e32 v24, v0
	v_mov_b32_e32 v25, v0
	v_mov_b32_e32 v26, v0
	v_mov_b32_e32 v27, v0
	v_mov_b32_e32 v28, v0
	v_mov_b32_e32 v29, v0
	v_mov_b32_e32 v30, v0
	v_mov_b32_e32 v31, v0
	v_mov_b32_e32 v40, v0
	v_mov_b32_e32 v41, v0
	v_mov_b32_e32 v42, v0
	v_mov_b32_e32 v43, v0
	v_mov_b32_e32 v44, v0
	v_mov_b32_e32 v45, v0
	v_mov_b32_e32 v46, v0
	v_mov_b32_e32 v47, v0
	v_mov_b32_e32 v56, v0
	v_mov_b32_e32 v57, v0
	v_mov_b32_e32 v58, v0
	v_mov_b32_e32 v59, v0
	v_mov_b32_e32 v60, v0
	v_mov_b32_e32 v61, v0
	v_mov_b32_e32 v62, v0
	v_mov_b32_e32 v63, v0
	v_mov_b32_e32 v64, v0
	v_mov_b32_e32 v65, v0
	v_mov_b32_e32 v66, v0
	v_mov_b32_e32 v67, v0
	v_mov_b32_e32 v68, v0
	v_mov_b32_e32 v69, v0
	v_mov_b32_e32 v70, v0
	v_mov_b32_e32 v71, v0
	v_mov_b32_e32 v80, v0
	v_mov_b32_e32 v81, v0
	v_mov_b32_e32 v82, v0
	v_mov_b32_e32 v83, v0
	v_mov_b32_e32 v84, v0
	v_mov_b32_e32 v85, v0
	v_mov_b32_e32 v86, v0
	v_mov_b32_e32 v87, v0
	v_mov_b32_e32 v96, v0
	v_mov_b32_e32 v97, v0
	v_mov_b32_e32 v98, v0
	v_mov_b32_e32 v99, v0
	v_mov_b32_e32 v100, v0
	v_mov_b32_e32 v101, v0
	v_mov_b32_e32 v102, v0
	v_mov_b32_e32 v103, v0
	v_mov_b32_e32 v112, v0
	v_mov_b32_e32 v113, v0
	v_mov_b32_e32 v114, v0
	v_mov_b32_e32 v115, v0
	v_mov_b32_e32 v116, v0
	v_mov_b32_e32 v117, v0
	v_mov_b32_e32 v118, v0
	v_mov_b32_e32 v119, v0
	v_mov_b32_e32 v72, v0
	v_mov_b32_e32 v73, v0
	v_mov_b32_e32 v74, v0
	v_mov_b32_e32 v75, v0
	v_mov_b32_e32 v76, v0
	v_mov_b32_e32 v77, v0
	v_mov_b32_e32 v78, v0
	v_mov_b32_e32 v79, v0
	v_mov_b32_e32 v88, v0
	v_mov_b32_e32 v89, v0
	v_mov_b32_e32 v90, v0
	v_mov_b32_e32 v91, v0
	v_mov_b32_e32 v92, v0
	v_mov_b32_e32 v93, v0
	v_mov_b32_e32 v94, v0
	v_mov_b32_e32 v95, v0
	v_mov_b32_e32 v104, v0
	v_mov_b32_e32 v105, v0
	v_mov_b32_e32 v106, v0
	v_mov_b32_e32 v107, v0
	v_mov_b32_e32 v108, v0
	v_mov_b32_e32 v109, v0
	v_mov_b32_e32 v110, v0
	v_mov_b32_e32 v111, v0
	v_mov_b32_e32 v120, v0
	v_mov_b32_e32 v121, v0
	v_mov_b32_e32 v122, v0
	v_mov_b32_e32 v123, v0
	v_mov_b32_e32 v124, v0
	v_mov_b32_e32 v125, v0
	v_mov_b32_e32 v126, v0
	v_mov_b32_e32 v127, v0
	v_readlane_b32 s36, v254, 6
	s_nop 3
	s_cmp_ge_u32 s36, 0x100
	s_cbranch_scc0 .Lsprio_p6
	s_setprio 1
.Lsprio_p6:
.LBB0_674:
	ds_read_b128 v[128:131], v174
	ds_read_b128 v[132:135], v174 offset:1024
	ds_read_b128 v[148:151], v174 offset:2048
	ds_read_b128 v[152:155], v174 offset:3072
	ds_read_b128 v[156:159], v175
	ds_read_b128 v[160:163], v175 offset:1024
	ds_read_b128 v[164:167], v175 offset:2048
	ds_read_b128 v[168:171], v175 offset:3072
	s_add_u32 s36, s24, 0x4000
	s_addc_u32 s37, s25, 0
	s_cmpk_eq_i32 s45, 0x7c
	s_cselect_b32 s40, s29, s36
	s_cselect_b32 s41, s3, s37
	s_cselect_b32 s38, s4, s30
	s_cselect_b32 s39, s5, s31
	s_add_u32 s36, s40, 0x8000
	s_addc_u32 s37, s41, 0
	s_add_u32 s46, s38, 0x200000
	s_addc_u32 s47, s39, 0
	s_mov_b32 m0, s94
	ds_read_b128 v[182:185], v176
	ds_read_b128 v[188:191], v176 offset:1024
	ds_read_b128 v[192:195], v176 offset:2048
	ds_read_b128 v[196:199], v176 offset:3072
	ds_read_b128 v[200:203], v176 offset:4096
	ds_read_b128 v[204:207], v176 offset:5120
	ds_read_b128 v[208:211], v176 offset:6144
	ds_read_b128 v[212:215], v176 offset:7168
	global_load_lds_dwordx4 v144, s[24:25]
	s_mov_b32 m0, s95
	s_nop 0
	global_load_lds_dwordx4 v146, s[24:25]
	s_waitcnt vmcnt(8)
	s_waitcnt lgkmcnt(0)
	s_barrier
	s_waitcnt lgkmcnt(0)
	v_mfma_f32_16x16x32_bf16 v[124:127], v[128:131], v[182:185], v[124:127]
	v_mfma_f32_16x16x32_bf16 v[120:123], v[148:151], v[182:185], v[120:123]
	v_mfma_f32_16x16x32_bf16 v[108:111], v[128:131], v[192:195], v[108:111]
	v_mfma_f32_16x16x32_bf16 v[104:107], v[148:151], v[192:195], v[104:107]
	v_mfma_f32_16x16x32_bf16 v[92:95], v[128:131], v[200:203], v[92:95]
	v_mfma_f32_16x16x32_bf16 v[88:91], v[148:151], v[200:203], v[88:91]
	v_mfma_f32_16x16x32_bf16 v[76:79], v[128:131], v[208:211], v[76:79]
	v_mfma_f32_16x16x32_bf16 v[72:75], v[148:151], v[208:211], v[72:75]
	v_mfma_f32_16x16x32_bf16 v[124:127], v[132:135], v[188:191], v[124:127]
	v_mfma_f32_16x16x32_bf16 v[120:123], v[152:155], v[188:191], v[120:123]
	v_mfma_f32_16x16x32_bf16 v[108:111], v[132:135], v[196:199], v[108:111]
	v_mfma_f32_16x16x32_bf16 v[104:107], v[152:155], v[196:199], v[104:107]
	v_mfma_f32_16x16x32_bf16 v[92:95], v[132:135], v[204:207], v[92:95]
	v_mfma_f32_16x16x32_bf16 v[88:91], v[152:155], v[204:207], v[88:91]
	v_mfma_f32_16x16x32_bf16 v[76:79], v[132:135], v[212:215], v[76:79]
	v_mfma_f32_16x16x32_bf16 v[72:75], v[152:155], v[212:215], v[72:75]
	v_mfma_f32_16x16x32_bf16 v[116:119], v[156:159], v[182:185], v[116:119]
	v_mfma_f32_16x16x32_bf16 v[112:115], v[164:167], v[182:185], v[112:115]
	v_mfma_f32_16x16x32_bf16 v[100:103], v[156:159], v[192:195], v[100:103]
	v_mfma_f32_16x16x32_bf16 v[96:99], v[164:167], v[192:195], v[96:99]
	v_mfma_f32_16x16x32_bf16 v[84:87], v[156:159], v[200:203], v[84:87]
	v_mfma_f32_16x16x32_bf16 v[80:83], v[164:167], v[200:203], v[80:83]
	v_mfma_f32_16x16x32_bf16 v[68:71], v[156:159], v[208:211], v[68:71]
	v_mfma_f32_16x16x32_bf16 v[64:67], v[164:167], v[208:211], v[64:67]
	v_mfma_f32_16x16x32_bf16 v[116:119], v[160:163], v[188:191], v[116:119]
	v_mfma_f32_16x16x32_bf16 v[112:115], v[168:171], v[188:191], v[112:115]
	v_mfma_f32_16x16x32_bf16 v[100:103], v[160:163], v[196:199], v[100:103]
	v_mfma_f32_16x16x32_bf16 v[96:99], v[168:171], v[196:199], v[96:99]
	v_mfma_f32_16x16x32_bf16 v[84:87], v[160:163], v[204:207], v[84:87]
	v_mfma_f32_16x16x32_bf16 v[80:83], v[168:171], v[204:207], v[80:83]
	v_mfma_f32_16x16x32_bf16 v[68:71], v[160:163], v[212:215], v[68:71]
	v_mfma_f32_16x16x32_bf16 v[64:67], v[168:171], v[212:215], v[64:67]
	s_barrier
	s_mov_b32 m0, s96
	s_add_u32 s98, s40, 0x4000
	s_addc_u32 s99, s41, 0
	ds_read_b128 v[182:185], v176 offset:16384
	ds_read_b128 v[188:191], v176 offset:17408
	ds_read_b128 v[192:195], v176 offset:18432
	ds_read_b128 v[196:199], v176 offset:19456
	ds_read_b128 v[200:203], v176 offset:20480
	ds_read_b128 v[204:207], v176 offset:21504
	ds_read_b128 v[208:211], v176 offset:22528
	ds_read_b128 v[212:215], v176 offset:23552
	global_load_lds_dwordx4 v138, s[38:39]
	s_mov_b32 m0, s97
	s_nop 0
	global_load_lds_dwordx4 v142, s[38:39]
	s_mov_b32 m0, s91
	s_nop 0
	global_load_lds_dwordx4 v138, s[46:47]
	s_mov_b32 m0, s26
	s_nop 0
	global_load_lds_dwordx4 v142, s[46:47]
	s_mov_b32 m0, s33
	s_nop 0
	global_load_lds_dwordx4 v136, s[40:41]
	s_mov_b32 m0, s88
	s_nop 0
	global_load_lds_dwordx4 v140, s[40:41]
	s_waitcnt vmcnt(8)
	s_waitcnt lgkmcnt(0)
	s_barrier
	s_waitcnt lgkmcnt(0)
	v_mfma_f32_16x16x32_bf16 v[60:63], v[128:131], v[182:185], v[60:63]
	v_mfma_f32_16x16x32_bf16 v[56:59], v[148:151], v[182:185], v[56:59]
	v_mfma_f32_16x16x32_bf16 v[44:47], v[128:131], v[192:195], v[44:47]
	v_mfma_f32_16x16x32_bf16 v[40:43], v[148:151], v[192:195], v[40:43]
	v_mfma_f32_16x16x32_bf16 v[28:31], v[128:131], v[200:203], v[28:31]
	v_mfma_f32_16x16x32_bf16 v[24:27], v[148:151], v[200:203], v[24:27]
	v_mfma_f32_16x16x32_bf16 v[12:15], v[128:131], v[208:211], v[12:15]
	v_mfma_f32_16x16x32_bf16 v[8:11], v[148:151], v[208:211], v[8:11]
	v_mfma_f32_16x16x32_bf16 v[60:63], v[132:135], v[188:191], v[60:63]
	v_mfma_f32_16x16x32_bf16 v[56:59], v[152:155], v[188:191], v[56:59]
	v_mfma_f32_16x16x32_bf16 v[44:47], v[132:135], v[196:199], v[44:47]
	v_mfma_f32_16x16x32_bf16 v[40:43], v[152:155], v[196:199], v[40:43]
	v_mfma_f32_16x16x32_bf16 v[28:31], v[132:135], v[204:207], v[28:31]
	v_mfma_f32_16x16x32_bf16 v[24:27], v[152:155], v[204:207], v[24:27]
	v_mfma_f32_16x16x32_bf16 v[12:15], v[132:135], v[212:215], v[12:15]
	v_mfma_f32_16x16x32_bf16 v[8:11], v[152:155], v[212:215], v[8:11]
	v_mfma_f32_16x16x32_bf16 v[52:55], v[156:159], v[182:185], v[52:55]
	v_mfma_f32_16x16x32_bf16 v[48:51], v[164:167], v[182:185], v[48:51]
	v_mfma_f32_16x16x32_bf16 v[36:39], v[156:159], v[192:195], v[36:39]
	v_mfma_f32_16x16x32_bf16 v[32:35], v[164:167], v[192:195], v[32:35]
	v_mfma_f32_16x16x32_bf16 v[20:23], v[156:159], v[200:203], v[20:23]
	v_mfma_f32_16x16x32_bf16 v[16:19], v[164:167], v[200:203], v[16:19]
	v_mfma_f32_16x16x32_bf16 v[4:7], v[156:159], v[208:211], v[4:7]
	v_mfma_f32_16x16x32_bf16 v[0:3], v[164:167], v[208:211], v[0:3]
	v_mfma_f32_16x16x32_bf16 v[52:55], v[160:163], v[188:191], v[52:55]
	v_mfma_f32_16x16x32_bf16 v[48:51], v[168:171], v[188:191], v[48:51]
	v_mfma_f32_16x16x32_bf16 v[36:39], v[160:163], v[196:199], v[36:39]
	v_mfma_f32_16x16x32_bf16 v[32:35], v[168:171], v[196:199], v[32:35]
	v_mfma_f32_16x16x32_bf16 v[20:23], v[160:163], v[204:207], v[20:23]
	v_mfma_f32_16x16x32_bf16 v[16:19], v[168:171], v[204:207], v[16:19]
	v_mfma_f32_16x16x32_bf16 v[4:7], v[160:163], v[212:215], v[4:7]
	v_mfma_f32_16x16x32_bf16 v[0:3], v[168:171], v[212:215], v[0:3]
	s_barrier
	ds_read_b128 v[128:131], v179
	ds_read_b128 v[132:135], v179 offset:1024
	ds_read_b128 v[148:151], v179 offset:2048
	ds_read_b128 v[152:155], v179 offset:3072
	ds_read_b128 v[156:159], v180
	ds_read_b128 v[160:163], v180 offset:1024
	ds_read_b128 v[164:167], v180 offset:2048
	ds_read_b128 v[168:171], v180 offset:3072
	s_mov_b32 m0, s89
	s_add_u32 s100, s38, 0x80
	s_addc_u32 s101, s39, 0
	ds_read_b128 v[182:185], v176 offset:32768
	ds_read_b128 v[188:191], v176 offset:33792
	ds_read_b128 v[192:195], v176 offset:34816
	ds_read_b128 v[196:199], v176 offset:35840
	ds_read_b128 v[200:203], v176 offset:36864
	ds_read_b128 v[204:207], v176 offset:37888
	ds_read_b128 v[208:211], v176 offset:38912
	ds_read_b128 v[212:215], v176 offset:39936
	global_load_lds_dwordx4 v136, s[98:99]
	s_mov_b32 m0, s90
	s_add_u32 s46, s38, 0x200080
	s_addc_u32 s47, s39, 0
	global_load_lds_dwordx4 v140, s[98:99]
	s_waitcnt vmcnt(8)
	s_waitcnt lgkmcnt(0)
	s_barrier
	s_waitcnt lgkmcnt(0)
	v_mfma_f32_16x16x32_bf16 v[124:127], v[128:131], v[182:185], v[124:127]
	v_mfma_f32_16x16x32_bf16 v[120:123], v[148:151], v[182:185], v[120:123]
	v_mfma_f32_16x16x32_bf16 v[108:111], v[128:131], v[192:195], v[108:111]
	v_mfma_f32_16x16x32_bf16 v[104:107], v[148:151], v[192:195], v[104:107]
	v_mfma_f32_16x16x32_bf16 v[92:95], v[128:131], v[200:203], v[92:95]
	v_mfma_f32_16x16x32_bf16 v[88:91], v[148:151], v[200:203], v[88:91]
	v_mfma_f32_16x16x32_bf16 v[76:79], v[128:131], v[208:211], v[76:79]
	v_mfma_f32_16x16x32_bf16 v[72:75], v[148:151], v[208:211], v[72:75]
	v_mfma_f32_16x16x32_bf16 v[124:127], v[132:135], v[188:191], v[124:127]
	v_mfma_f32_16x16x32_bf16 v[120:123], v[152:155], v[188:191], v[120:123]
	v_mfma_f32_16x16x32_bf16 v[108:111], v[132:135], v[196:199], v[108:111]
	v_mfma_f32_16x16x32_bf16 v[104:107], v[152:155], v[196:199], v[104:107]
	v_mfma_f32_16x16x32_bf16 v[92:95], v[132:135], v[204:207], v[92:95]
	v_mfma_f32_16x16x32_bf16 v[88:91], v[152:155], v[204:207], v[88:91]
	v_mfma_f32_16x16x32_bf16 v[76:79], v[132:135], v[212:215], v[76:79]
	v_mfma_f32_16x16x32_bf16 v[72:75], v[152:155], v[212:215], v[72:75]
	v_mfma_f32_16x16x32_bf16 v[116:119], v[156:159], v[182:185], v[116:119]
	v_mfma_f32_16x16x32_bf16 v[112:115], v[164:167], v[182:185], v[112:115]
	v_mfma_f32_16x16x32_bf16 v[100:103], v[156:159], v[192:195], v[100:103]
	v_mfma_f32_16x16x32_bf16 v[96:99], v[164:167], v[192:195], v[96:99]
	v_mfma_f32_16x16x32_bf16 v[84:87], v[156:159], v[200:203], v[84:87]
	v_mfma_f32_16x16x32_bf16 v[80:83], v[164:167], v[200:203], v[80:83]
	v_mfma_f32_16x16x32_bf16 v[68:71], v[156:159], v[208:211], v[68:71]
	v_mfma_f32_16x16x32_bf16 v[64:67], v[164:167], v[208:211], v[64:67]
	v_mfma_f32_16x16x32_bf16 v[116:119], v[160:163], v[188:191], v[116:119]
	v_mfma_f32_16x16x32_bf16 v[112:115], v[168:171], v[188:191], v[112:115]
	v_mfma_f32_16x16x32_bf16 v[100:103], v[160:163], v[196:199], v[100:103]
	v_mfma_f32_16x16x32_bf16 v[96:99], v[168:171], v[196:199], v[96:99]
	v_mfma_f32_16x16x32_bf16 v[84:87], v[160:163], v[204:207], v[84:87]
	v_mfma_f32_16x16x32_bf16 v[80:83], v[168:171], v[204:207], v[80:83]
	v_mfma_f32_16x16x32_bf16 v[68:71], v[160:163], v[212:215], v[68:71]
	v_mfma_f32_16x16x32_bf16 v[64:67], v[168:171], v[212:215], v[64:67]
	s_barrier
	s_mov_b32 m0, s27
	s_nop 0
	ds_read_b128 v[182:185], v176 offset:49152
	ds_read_b128 v[188:191], v176 offset:50176
	ds_read_b128 v[192:195], v176 offset:51200
	ds_read_b128 v[196:199], v176 offset:52224
	ds_read_b128 v[200:203], v176 offset:53248
	ds_read_b128 v[204:207], v176 offset:54272
	ds_read_b128 v[208:211], v176 offset:55296
	ds_read_b128 v[212:215], v176 offset:56320
	global_load_lds_dwordx4 v138, s[100:101]
	s_mov_b32 m0, s34
	s_nop 0
	global_load_lds_dwordx4 v142, s[100:101]
	s_mov_b32 m0, s35
	s_nop 0
	global_load_lds_dwordx4 v138, s[46:47]
	s_mov_b32 m0, s28
	s_nop 0
	global_load_lds_dwordx4 v142, s[46:47]
	s_mov_b32 m0, s92
	s_nop 0
	global_load_lds_dwordx4 v136, s[36:37]
	s_mov_b32 m0, s93
	s_nop 0
	global_load_lds_dwordx4 v140, s[36:37]
	s_waitcnt vmcnt(8)
	s_waitcnt lgkmcnt(0)
	s_barrier
	s_waitcnt lgkmcnt(0)
	v_mfma_f32_16x16x32_bf16 v[60:63], v[128:131], v[182:185], v[60:63]
	v_mfma_f32_16x16x32_bf16 v[56:59], v[148:151], v[182:185], v[56:59]
	v_mfma_f32_16x16x32_bf16 v[44:47], v[128:131], v[192:195], v[44:47]
	v_mfma_f32_16x16x32_bf16 v[40:43], v[148:151], v[192:195], v[40:43]
	v_mfma_f32_16x16x32_bf16 v[28:31], v[128:131], v[200:203], v[28:31]
	v_mfma_f32_16x16x32_bf16 v[24:27], v[148:151], v[200:203], v[24:27]
	v_mfma_f32_16x16x32_bf16 v[12:15], v[128:131], v[208:211], v[12:15]
	v_mfma_f32_16x16x32_bf16 v[8:11], v[148:151], v[208:211], v[8:11]
	v_mfma_f32_16x16x32_bf16 v[60:63], v[132:135], v[188:191], v[60:63]
	v_mfma_f32_16x16x32_bf16 v[56:59], v[152:155], v[188:191], v[56:59]
	v_mfma_f32_16x16x32_bf16 v[44:47], v[132:135], v[196:199], v[44:47]
	v_mfma_f32_16x16x32_bf16 v[40:43], v[152:155], v[196:199], v[40:43]
	v_mfma_f32_16x16x32_bf16 v[28:31], v[132:135], v[204:207], v[28:31]
	v_mfma_f32_16x16x32_bf16 v[24:27], v[152:155], v[204:207], v[24:27]
	v_mfma_f32_16x16x32_bf16 v[12:15], v[132:135], v[212:215], v[12:15]
	v_mfma_f32_16x16x32_bf16 v[8:11], v[152:155], v[212:215], v[8:11]
	v_mfma_f32_16x16x32_bf16 v[52:55], v[156:159], v[182:185], v[52:55]
	v_mfma_f32_16x16x32_bf16 v[48:51], v[164:167], v[182:185], v[48:51]
	v_mfma_f32_16x16x32_bf16 v[36:39], v[156:159], v[192:195], v[36:39]
	v_mfma_f32_16x16x32_bf16 v[32:35], v[164:167], v[192:195], v[32:35]
	v_mfma_f32_16x16x32_bf16 v[20:23], v[156:159], v[200:203], v[20:23]
	v_mfma_f32_16x16x32_bf16 v[16:19], v[164:167], v[200:203], v[16:19]
	v_mfma_f32_16x16x32_bf16 v[4:7], v[156:159], v[208:211], v[4:7]
	v_mfma_f32_16x16x32_bf16 v[0:3], v[164:167], v[208:211], v[0:3]
	v_mfma_f32_16x16x32_bf16 v[52:55], v[160:163], v[188:191], v[52:55]
	v_mfma_f32_16x16x32_bf16 v[48:51], v[168:171], v[188:191], v[48:51]
	v_mfma_f32_16x16x32_bf16 v[36:39], v[160:163], v[196:199], v[36:39]
	v_mfma_f32_16x16x32_bf16 v[32:35], v[168:171], v[196:199], v[32:35]
	v_mfma_f32_16x16x32_bf16 v[20:23], v[160:163], v[204:207], v[20:23]
	v_mfma_f32_16x16x32_bf16 v[16:19], v[168:171], v[204:207], v[16:19]
	v_mfma_f32_16x16x32_bf16 v[4:7], v[160:163], v[212:215], v[4:7]
	v_mfma_f32_16x16x32_bf16 v[0:3], v[168:171], v[212:215], v[0:3]
	s_barrier
	s_add_i32 s45, s45, 2
	s_add_u32 s30, s30, 0x100
	s_addc_u32 s31, s31, 0
	s_add_u32 s24, s24, 0x10000
	s_addc_u32 s25, s25, 0
	s_cmpk_gt_u32 s45, 0x7d
	s_cbranch_scc0 .LBB0_674
	s_setprio 0
	s_and_b64 vcc, exec, s[78:79]
	s_cbranch_vccz .LBB0_677
	s_barrier
